# attention work queue: next unit index requested one unit ahead (on top of the pipelined attn_sample loop)
# baseline (speedup 1.0000x reference)
.LBB0_794:
	s_or_b64 exec, exec, s[10:11]
	v_lshlrev_b32_e32 v2, 1, v66
	v_lshlrev_b32_e32 v4, 2, v66
	v_and_b32_e32 v5, 4, v64
	s_lshl_b32 s12, s35, 14
	v_and_b32_e32 v3, 48, v2
	v_and_b32_e32 v4, 8, v4
	v_and_or_b32 v2, v2, 2, v5
	s_add_i32 s12, s12, 0
	v_or3_b32 v2, v2, v4, v3
	v_and_b32_e32 v180, 31, v64
	v_mov_b32_e32 v3, s12
	v_lshl_add_u32 v181, v2, 1, s12
	s_movk_i32 s12, 0x90
	v_lshrrev_b32_e32 v1, 5, v66
	v_mad_u32_u24 v203, v180, s12, v3
	v_not_b32_e32 v3, 16
	v_mad_i32_i24 v217, v1, -4, v3
	v_not_b32_e32 v3, 17
	v_mad_i32_i24 v218, v1, -4, v3
	v_not_b32_e32 v3, 18
	v_mad_i32_i24 v219, v1, -4, v3
	v_not_b32_e32 v3, 23
	v_lshlrev_b32_e32 v0, 3, v1
	v_mad_i32_i24 v220, v1, -4, v3
	v_not_b32_e32 v3, 24
	v_or_b32_e32 v2, 16, v0
	v_mad_i32_i24 v221, v1, -4, v3
	v_not_b32_e32 v3, 25
	v_lshlrev_b32_e32 v182, 1, v0
	v_mbcnt_lo_u32_b32 v0, -1, 0
	v_mad_i32_i24 v222, v1, -4, v3
	v_not_b32_e32 v3, 26
	v_mbcnt_hi_u32_b32 v207, -1, v0
	v_mov_b32_e32 v183, 0
	v_mul_i32_i24_e32 v202, -4, v1
	v_lshlrev_b32_e32 v204, 4, v1
	v_mad_i32_i24 v205, v1, -4, -1
	v_mad_i32_i24 v210, v1, -4, -2
	v_mad_i32_i24 v211, v1, -4, -3
	v_mad_i32_i24 v212, v1, -4, -8
	v_mad_i32_i24 v213, v1, -4, -9
	v_mad_i32_i24 v214, v1, -4, -10
	v_mad_i32_i24 v215, v1, -4, -11
	v_mad_i32_i24 v216, v1, -4, -16
	v_mad_i32_i24 v223, v1, -4, v3
	v_mul_u32_u24_e32 v224, 0x480, v1
	v_mul_u32_u24_e32 v225, 0x90, v2
	v_lshlrev_b32_e32 v2, 2, v1
	v_mad_i32_i24 v226, v1, -4, v180
	v_lshrrev_b32_e32 v1, 1, v64
	s_movk_i32 s17, 0x2c00
	v_mov_b64_e32 v[4:5], s[38:39]
	v_and_b32_e32 v0, 64, v207
	s_mov_b32 s15, 0
	v_cmp_eq_u32_e64 s[10:11], 0, v66
	v_lshlrev_b32_e32 v184, 1, v180
	v_mov_b32_e32 v185, v183
	v_and_b32_e32 v186, 16, v1
	v_mov_b32_e32 v187, v183
	v_mad_u64_u32 v[188:189], s[12:13], v180, s17, v[4:5]
	s_mov_b32 s26, 0x58000
	s_mov_b32 s27, 0x11f00000
	s_movk_i32 s28, 0xff80
	s_movk_i32 s29, 0xffa0
	s_mov_b32 s16, 0x3e38aa3b
	s_mov_b32 s30, 0xc2fc0000
	s_mov_b32 s31, 0xffff0000
	s_mov_b64 s[18:19], 0xb0000
	s_movk_i32 s35, 0x3000
	v_lshlrev_b32_e32 v190, 1, v2
	v_mov_b32_e32 v227, 0x2c00
	v_xor_b32_e32 v208, 32, v207
	v_add_u32_e32 v209, 64, v0
	v_mov_b32_e32 v228, 0x80
	v_mov_b32_e32 v229, 0xa0
	v_mov_b32_e32 v230, 0x42800000
	v_not_b32_e32 v231, 63
	s_waitcnt lgkmcnt(0)
	s_barrier
	s_and_saveexec_b64 s[12:13], s[10:11]
	v_mov_b32_e32 v255, 1
	s_nop 0
	global_atomic_add v255, v183, v255, s[38:39] offset:4 sc0
	s_or_b64 exec, exec, s[12:13]
	s_branch .LBB0_797

.LBB0_797:
	s_waitcnt vmcnt(0)
	v_readfirstlane_b32 s43, v255
	s_and_saveexec_b64 s[12:13], s[10:11]
	v_mov_b32_e32 v255, 1
	s_nop 0
	global_atomic_add v255, v183, v255, s[38:39] offset:4 sc0
	s_or_b64 exec, exec, s[12:13]
	s_cmpk_gt_i32 s43, 0x3fff
	s_mov_b64 s[12:13], -1
	s_cbranch_scc1 .LBB0_796
	s_ashr_i32 s12, s43, 9
	s_bfe_u32 s52, s43, 0x50001
	s_ashr_i32 s13, s12, 31
	s_lshl_b32 s14, s43, 5
	s_lshl_b64 s[20:21], s[12:13], 11
	s_lshl_b32 s13, s52, 6
	s_and_b32 s25, s14, 32
	s_or_b32 s13, s13, s25
	v_or_b32_e32 v0, s13, v180
	v_or_b32_e32 v2, s20, v0
	v_mov_b64_e32 v[0:1], s[50:51]
	v_mad_u64_u32 v[2:3], s[40:41], v2, s17, v[0:1]
	v_sub_u32_e64 v4, 8, s52 clamp
	s_bfe_u32 s42, s43, 0x30006
	s_add_i32 s41, s52, -8
	v_readfirstlane_b32 s13, v4
	s_mul_i32 s24, s42, 0x404
	s_add_i32 s54, s41, s13
	v_mad_i32_i24 v3, s21, v227, v3
	s_lshl_b32 s14, s42, 7
	s_add_i32 s24, s24, 0
	s_ashr_i32 s55, s54, 31
	v_lshl_add_u64 v[192:193], v[2:3], 0, s[14:15]
	s_add_i32 s24, s24, 0x20000
	s_lshl_b64 s[54:55], s[54:55], 6
	v_lshl_add_u64 v[2:3], v[192:193], 0, v[182:183]
	s_add_u32 s13, s54, s20
	global_load_dwordx4 v[108:111], v[2:3], off
	global_load_dwordx4 v[104:107], v[2:3], off offset:32
	global_load_dwordx4 v[100:103], v[2:3], off offset:64
	global_load_dwordx4 v[96:99], v[2:3], off offset:96
	v_or_b32_e32 v2, s13, v180
	s_addc_u32 s40, s55, s21
	v_mad_u64_u32 v[0:1], s[54:55], v2, s17, v[0:1]
	v_mad_i32_i24 v1, s40, v227, v1
	v_lshl_add_u64 v[0:1], v[0:1], 0, s[14:15]
	v_lshl_add_u64 v[0:1], v[0:1], 0, v[182:183]
	v_add_co_u32_e32 v2, vcc, s26, v0
	v_readfirstlane_b32 s40, v4
	s_nop 0
	v_addc_co_u32_e32 v3, vcc, 0, v1, vcc
	global_load_dwordx4 v[52:55], v[0:1], off offset:1024
	global_load_dwordx4 v[48:51], v[0:1], off offset:1056
	global_load_dwordx4 v[56:59], v[2:3], off offset:1024
	global_load_dwordx4 v[44:47], v[2:3], off offset:1056
	global_load_dwordx4 v[40:43], v[0:1], off offset:1088
	global_load_dwordx4 v[32:35], v[0:1], off offset:1120
	global_load_dwordx4 v[36:39], v[2:3], off offset:1088
	global_load_dwordx4 v[176:179], v[2:3], off offset:1120
	v_mov_b32_e32 v0, s24
	ds_read_b32 v194, v0 offset:1024
	v_cmp_lt_i32_e32 vcc, v208, v209
	s_cmp_eq_u32 s52, 0
	s_nop 0
	v_cndmask_b32_e32 v0, v207, v208, vcc
	v_lshlrev_b32_e32 v191, 2, v0
	s_cbranch_scc1 .LBB0_813
	s_min_u32 s13, s52, 8
	s_sub_i32 s52, s52, s13
	s_ashr_i32 s53, s52, 31
	s_lshl_b32 s14, s13, 6
	s_lshl_b64 s[54:55], s[52:53], 6
	s_add_u32 s54, s54, s20
	s_addc_u32 s55, s55, s21
	s_lshl_b32 s13, s43, 1
	s_and_b32 s43, s13, 0x380
	v_lshl_add_u64 v[0:1], s[54:55], 0, v[184:185]
	s_add_u32 s54, s38, s43
	s_addc_u32 s55, s39, 0
	s_mul_hi_i32 s13, s12, 0x1600000
	s_mul_i32 s12, s12, 0x1600000
	s_mul_hi_i32 s53, s52, 0xb0000
	s_mul_i32 s52, s52, 0xb0000
	v_mov_b64_e32 v[2:3], s[54:55]
	s_add_u32 s12, s12, s52
	v_mad_u64_u32 v[198:199], s[54:55], v0, s17, v[2:3]
	s_addc_u32 s13, s13, s53
	s_or_b32 s12, s12, s43
	v_mov_b32_e32 v233, 0
	s_waitcnt vmcnt(0)
	v_mov_b64_e32 v[112:113], v[176:177]
	v_mov_b64_e32 v[118:119], v[34:35]
	v_mov_b64_e32 v[126:127], v[38:39]
	v_mov_b64_e32 v[122:123], v[42:43]
	v_mov_b64_e32 v[130:131], v[46:47]
	v_mov_b64_e32 v[134:135], v[50:51]
	v_mov_b64_e32 v[142:143], v[58:59]
	v_mov_b64_e32 v[138:139], v[54:55]
	s_waitcnt lgkmcnt(0)
	v_mov_b32_e32 v196, v194
	v_mov_b32_e32 v197, v194
	v_add_u32_e32 v232, s25, v226
	v_mad_i32_i24 v199, v1, s17, v199
	v_lshl_add_u64 v[200:201], v[188:189], 0, s[12:13]
	v_mov_b32_e32 v234, 0xf149f2ca
	s_mov_b32 s43, 0
	v_mov_b32_e32 v16, 0
	v_mov_b32_e32 v17, v233
	v_mov_b32_e32 v18, v233
	v_mov_b32_e32 v19, v233
	v_mov_b32_e32 v20, v233
	v_mov_b32_e32 v21, v233
	v_mov_b32_e32 v22, v233
	v_mov_b32_e32 v23, v233
	v_mov_b32_e32 v24, v233
	v_mov_b32_e32 v25, v233
	v_mov_b32_e32 v26, v233
	v_mov_b32_e32 v27, v233
	v_mov_b32_e32 v28, v233
	v_mov_b32_e32 v29, v233
	v_mov_b32_e32 v30, v233
	v_mov_b32_e32 v31, v233
	v_mov_b32_e32 v0, 0
	v_mov_b32_e32 v1, v233
	v_mov_b32_e32 v2, v233
	v_mov_b32_e32 v3, v233
	v_mov_b32_e32 v4, v233
	v_mov_b32_e32 v5, v233
	v_mov_b32_e32 v6, v233
	v_mov_b32_e32 v7, v233
	v_mov_b32_e32 v8, v233
	v_mov_b32_e32 v9, v233
	v_mov_b32_e32 v10, v233
	v_mov_b32_e32 v11, v233
	v_mov_b32_e32 v12, v233
	v_mov_b32_e32 v13, v233
	v_mov_b32_e32 v14, v233
	v_mov_b32_e32 v15, v233
	v_mov_b64_e32 v[114:115], v[178:179]
	v_mov_b64_e32 v[116:117], v[32:33]
	v_mov_b64_e32 v[124:125], v[36:37]
	v_mov_b64_e32 v[120:121], v[40:41]
	v_mov_b64_e32 v[128:129], v[44:45]
	v_mov_b64_e32 v[132:133], v[48:49]
	v_mov_b64_e32 v[140:141], v[56:57]
	v_mov_b64_e32 v[136:137], v[52:53]
